# pipelined EpiRes residual epilogue (12-deep ring, counted vmcnt) + NA rpb bias reads de-serialized + norm phases skip split-K partial path for clamped dummy rows
# speedup vs baseline: 1.0206x; 1.0206x over previous
.LBB0_180:
	s_and_b64 vcc, exec, s[0:1]
	s_cbranch_vccz .LBB0_216
	s_cmp_ge_u32 s15, s8
	s_cselect_b64 s[0:1], -1, 0
	s_cmp_lt_u32 s15, s11
	s_cselect_b64 s[18:19], -1, 0
	s_and_b64 s[0:1], s[0:1], s[18:19]
	s_andn2_b64 vcc, exec, s[0:1]
	s_cbranch_vccnz .LBB0_217
	v_add_u32_e32 v14, v14, v148
	ds_read_b128 v[10:13], v14
	v_cmp_lt_u32_e32 vcc, s15, v145
	v_cmp_ge_u32_e64 s[0:1], s15, v150
	s_or_b64 s[0:1], vcc, s[0:1]
	s_or_b64 s[18:19], s[0:1], s[72:73]
	s_nor_b64 s[18:19], s[18:19], s[74:75]
	v_mov_b32_e32 v64, 0xf149f2ca
	s_waitcnt lgkmcnt(0)
	v_mfma_f32_32x32x16_bf16 v[48:63], v[10:13], v[80:83], 0
	ds_read_b128 v[10:13], v14 offset:32
	s_waitcnt lgkmcnt(0)
	v_mfma_f32_32x32x16_bf16 v[48:63], v[10:13], v[84:87], v[48:63]
	ds_read_b128 v[10:13], v14 offset:64
	s_waitcnt lgkmcnt(0)
	v_mfma_f32_32x32x16_bf16 v[48:63], v[10:13], v[88:91], v[48:63]
	ds_read_b128 v[10:13], v14 offset:96
	v_mov_b32_e32 v14, 0xf149f2ca
	s_waitcnt lgkmcnt(0)
	v_mfma_f32_32x32x16_bf16 v[48:63], v[10:13], v[92:95], v[48:63]
	ds_read_b32 v201, v152
	ds_read_b32 v202, v152 offset:4
	ds_read_b32 v203, v152 offset:8
	ds_read_b32 v204, v152 offset:12
	ds_read_b32 v205, v152 offset:32
	ds_read_b32 v206, v152 offset:36
	ds_read_b32 v207, v152 offset:40
	ds_read_b32 v208, v152 offset:44
	ds_read_b32 v209, v152 offset:64
	ds_read_b32 v210, v152 offset:68
	ds_read_b32 v211, v152 offset:72
	ds_read_b32 v212, v152 offset:76
	ds_read_b32 v213, v152 offset:96
	ds_read_b32 v214, v152 offset:100
	ds_read_b32 v215, v152 offset:104
	ds_read_b32 v216, v152 offset:108
	v_mov_b32_e32 v217, 0xf149f2ca
	s_waitcnt lgkmcnt(12)
	v_add_f32_e32 v201, v48, v201
	s_mov_b64 vcc, s[18:19]
	v_sub_f32_e32 v201, v201, v15
	v_cndmask_b32_e32 v64, v217, v201, vcc
	v_add_f32_e32 v202, v49, v202
	s_nor_b64 vcc, s[0:1], s[2:3]
	v_sub_f32_e32 v202, v202, v15
	v_cndmask_b32_e32 v14, v217, v202, vcc
	v_add_f32_e32 v203, v50, v203
	s_nor_b64 vcc, s[0:1], s[22:23]
	v_sub_f32_e32 v203, v203, v15
	v_cndmask_b32_e32 v66, v217, v203, vcc
	v_add_f32_e32 v204, v51, v204
	s_nor_b64 vcc, s[0:1], s[24:25]
	v_sub_f32_e32 v204, v204, v15
	v_cndmask_b32_e32 v65, v217, v204, vcc
	s_waitcnt lgkmcnt(8)
	v_add_f32_e32 v205, v52, v205
	s_nor_b64 vcc, s[0:1], s[30:31]
	v_sub_f32_e32 v205, v205, v15
	v_cndmask_b32_e32 v68, v217, v205, vcc
	v_add_f32_e32 v206, v53, v206
	s_nor_b64 vcc, s[0:1], s[34:35]
	v_sub_f32_e32 v206, v206, v15
	v_cndmask_b32_e32 v67, v217, v206, vcc
	v_add_f32_e32 v207, v54, v207
	s_nor_b64 vcc, s[0:1], s[40:41]
	v_sub_f32_e32 v207, v207, v15
	v_cndmask_b32_e32 v70, v217, v207, vcc
	v_add_f32_e32 v208, v55, v208
	s_nor_b64 vcc, s[0:1], s[42:43]
	v_sub_f32_e32 v208, v208, v15
	v_cndmask_b32_e32 v69, v217, v208, vcc
	s_waitcnt lgkmcnt(4)
	v_add_f32_e32 v209, v56, v209
	s_nor_b64 vcc, s[0:1], s[94:95]
	v_sub_f32_e32 v209, v209, v15
	v_cndmask_b32_e32 v72, v217, v209, vcc
	v_add_f32_e32 v210, v57, v210
	s_nor_b64 vcc, s[0:1], s[38:39]
	v_sub_f32_e32 v210, v210, v15
	v_cndmask_b32_e32 v71, v217, v210, vcc
	v_add_f32_e32 v211, v58, v211
	s_nor_b64 vcc, s[0:1], s[36:37]
	v_sub_f32_e32 v211, v211, v15
	v_cndmask_b32_e32 v74, v217, v211, vcc
	v_add_f32_e32 v212, v59, v212
	s_nor_b64 vcc, s[0:1], s[50:51]
	v_sub_f32_e32 v212, v212, v15
	v_cndmask_b32_e32 v73, v217, v212, vcc
	s_waitcnt lgkmcnt(0)
	v_add_f32_e32 v213, v60, v213
	s_nor_b64 vcc, s[0:1], s[76:77]
	v_sub_f32_e32 v213, v213, v15
	v_cndmask_b32_e32 v76, v217, v213, vcc
	v_add_f32_e32 v214, v61, v214
	s_nor_b64 vcc, s[0:1], s[78:79]
	v_sub_f32_e32 v214, v214, v15
	v_cndmask_b32_e32 v75, v217, v214, vcc
	v_add_f32_e32 v215, v62, v215
	s_nor_b64 vcc, s[0:1], s[80:81]
	v_sub_f32_e32 v215, v215, v15
	v_cndmask_b32_e32 v78, v217, v215, vcc
	v_add_f32_e32 v216, v63, v216
	s_nor_b64 vcc, s[0:1], s[44:45]
	v_sub_f32_e32 v216, v216, v15
	v_cndmask_b32_e32 v77, v217, v216, vcc
	v_exp_f32_e32 v10, v64
	v_exp_f32_e32 v11, v14
	v_exp_f32_e32 v12, v66
	v_exp_f32_e32 v13, v65
	v_exp_f32_e32 v48, v68
	v_exp_f32_e32 v49, v67
	v_exp_f32_e32 v50, v70
	v_exp_f32_e32 v51, v69
	v_pk_add_f32 v[52:53], v[10:11], 0 op_sel_hi:[1,0]
	v_exp_f32_e32 v54, v74
	v_pk_add_f32 v[52:53], v[52:53], v[12:13]
	v_exp_f32_e32 v55, v73
	v_pk_add_f32 v[52:53], v[52:53], v[48:49]
	v_exp_f32_e32 v56, v76
	v_pk_add_f32 v[60:61], v[52:53], v[50:51]
	v_exp_f32_e32 v52, v72
	v_exp_f32_e32 v53, v71
	v_exp_f32_e32 v57, v75
	v_exp_f32_e32 v58, v78
	v_exp_f32_e32 v59, v77
	v_pk_add_f32 v[60:61], v[60:61], v[52:53]
	s_mov_b32 s0, 0x47800000
	v_pk_add_f32 v[60:61], v[60:61], v[54:55]
	s_nop 0
	v_pk_add_f32 v[60:61], v[60:61], v[56:57]
	s_nop 0
	v_pk_add_f32 v[60:61], v[60:61], v[58:59]
	s_nop 0
	v_pk_add_f32 v[60:61], v[60:61], v[60:61] op_sel:[0,1] op_sel_hi:[1,0]
	s_nop 0
	v_cmp_nge_f32_e32 vcc, s0, v60
	v_cmp_eq_u16_sdwa s[0:1], v153, v1 src0_sel:BYTE_0 src1_sel:DWORD
	s_or_b64 vcc, vcc, s[0:1]
	s_cbranch_vccz .LBB0_221
	v_max_f32_e32 v10, v14, v14
	v_max_f32_e32 v11, v64, v64
	v_max_f32_e32 v10, v11, v10
	v_max3_f32 v10, v10, v66, v65
	v_max3_f32 v10, v10, v68, v67
	v_max3_f32 v10, v10, v70, v69
	v_and_b32_e32 v12, 64, v220
	v_max3_f32 v10, v10, v72, v71
	v_xor_b32_e32 v11, 32, v220
	v_add_u32_e32 v12, 64, v12
	v_max3_f32 v10, v10, v74, v73
	v_cmp_lt_i32_e32 vcc, v11, v12
	v_max3_f32 v10, v10, v76, v75
	v_max3_f32 v10, v10, v78, v77
	v_cndmask_b32_e32 v11, v220, v11, vcc
	v_lshlrev_b32_e32 v11, 2, v11
	ds_bpermute_b32 v11, v11, v10
	s_mov_b32 s0, 0xefa18f08
	s_waitcnt lgkmcnt(0)
	v_max_f32_e32 v11, v11, v11
	v_max_f32_e32 v10, v10, v11
	v_and_b32_e32 v11, 1, v153
	v_cmp_lt_f32_e32 vcc, s0, v10
	v_max_f32_e32 v12, 0, v10
	v_cmp_eq_u32_e64 s[0:1], 1, v11
	v_cndmask_b32_e32 v10, 0, v10, vcc
	s_nop 0
	v_cndmask_b32_e64 v61, v10, v12, s[0:1]
	v_exp_f32_e64 v10, -v61
	v_sub_f32_e32 v12, v66, v61
	v_sub_f32_e32 v13, v65, v61
	v_exp_f32_e32 v12, v12
	v_cndmask_b32_e64 v10, 1.0, v10, s[0:1]
	v_mul_f32_e32 v151, v151, v10
	v_pk_mul_f32 v[30:31], v[30:31], v[10:11] op_sel_hi:[1,0]
	v_pk_mul_f32 v[28:29], v[28:29], v[10:11] op_sel_hi:[1,0]
	v_pk_mul_f32 v[26:27], v[26:27], v[10:11] op_sel_hi:[1,0]
	v_pk_mul_f32 v[24:25], v[24:25], v[10:11] op_sel_hi:[1,0]
	v_pk_mul_f32 v[22:23], v[22:23], v[10:11] op_sel_hi:[1,0]
	v_pk_mul_f32 v[20:21], v[20:21], v[10:11] op_sel_hi:[1,0]
	v_pk_mul_f32 v[18:19], v[18:19], v[10:11] op_sel_hi:[1,0]
	v_pk_mul_f32 v[16:17], v[16:17], v[10:11] op_sel_hi:[1,0]
	v_pk_mul_f32 v[46:47], v[46:47], v[10:11] op_sel_hi:[1,0]
	v_pk_mul_f32 v[44:45], v[44:45], v[10:11] op_sel_hi:[1,0]
	v_pk_mul_f32 v[42:43], v[42:43], v[10:11] op_sel_hi:[1,0]
	v_pk_mul_f32 v[40:41], v[40:41], v[10:11] op_sel_hi:[1,0]
	v_pk_mul_f32 v[38:39], v[38:39], v[10:11] op_sel_hi:[1,0]
	v_pk_mul_f32 v[36:37], v[36:37], v[10:11] op_sel_hi:[1,0]
	v_pk_mul_f32 v[34:35], v[34:35], v[10:11] op_sel_hi:[1,0]
	v_pk_mul_f32 v[32:33], v[32:33], v[10:11] op_sel_hi:[1,0]
	v_sub_f32_e32 v10, v64, v61
	v_sub_f32_e32 v11, v14, v61
	v_sub_f32_e32 v14, v68, v61
	v_exp_f32_e32 v10, v10
	v_exp_f32_e32 v11, v11
	v_exp_f32_e32 v48, v14
	v_sub_f32_e32 v14, v67, v61
	v_exp_f32_e32 v13, v13
	v_exp_f32_e32 v49, v14
	v_sub_f32_e32 v14, v70, v61
	v_exp_f32_e32 v50, v14
	v_sub_f32_e32 v14, v69, v61
	v_exp_f32_e32 v51, v14
	v_pk_add_f32 v[52:53], v[10:11], 0 op_sel_hi:[1,0]
	v_sub_f32_e32 v14, v72, v61
	v_pk_add_f32 v[52:53], v[12:13], v[52:53]
	s_or_b64 s[0:1], vcc, s[0:1]
	v_pk_add_f32 v[52:53], v[48:49], v[52:53]
	v_cndmask_b32_e64 v153, 0, 1, s[0:1]
	v_pk_add_f32 v[62:63], v[50:51], v[52:53]
	v_exp_f32_e32 v52, v14
	v_sub_f32_e32 v14, v71, v61
	v_exp_f32_e32 v53, v14
	v_sub_f32_e32 v14, v74, v61
	v_exp_f32_e32 v54, v14
	v_sub_f32_e32 v14, v73, v61
	v_exp_f32_e32 v55, v14
	v_sub_f32_e32 v14, v76, v61
	v_exp_f32_e32 v56, v14
	v_sub_f32_e32 v14, v75, v61
	v_exp_f32_e32 v57, v14
	v_sub_f32_e32 v14, v78, v61
	v_exp_f32_e32 v58, v14
	v_sub_f32_e32 v14, v77, v61
	v_exp_f32_e32 v59, v14
	v_pk_add_f32 v[62:63], v[52:53], v[62:63]
	s_nop 0
	v_pk_add_f32 v[62:63], v[54:55], v[62:63]
	s_nop 0
	v_pk_add_f32 v[62:63], v[56:57], v[62:63]
	s_nop 0
	v_pk_add_f32 v[62:63], v[58:59], v[62:63]
	s_nop 0
	v_mov_b32_e32 v14, v62
	v_mov_b32_e32 v60, v63
	v_pk_add_f32 v[14:15], v[14:15], v[60:61]
	s_branch .LBB0_222

.LBB0_445:
	s_or_b64 exec, exec, s[36:37]
	v_add_u32_e32 v96, s5, v66
	v_readlane_b32 s56, v254, 4
	v_min_i32_e32 v6, s6, v96
	v_readlane_b32 s71, v254, 19
	v_ashrrev_i32_e32 v2, 31, v6
	v_add_u32_e32 v0, 0xffff8000, v6
	v_cmp_gt_i32_e32 vcc, s40, v6
	v_mov_b32_e32 v4, s55
	v_readlane_b32 s70, v254, 18
	v_mov_b32_e32 v5, s71
	v_cndmask_b32_e32 v3, 0, v2, vcc
	v_cndmask_b32_e32 v2, v0, v6, vcc
	v_cndmask_b32_e32 v5, v4, v5, vcc
	v_mov_b32_e32 v4, s54
	v_mov_b32_e32 v7, s70
	v_cndmask_b32_e32 v4, v4, v7, vcc
	v_lshlrev_b64 v[2:3], 12, v[2:3]
	v_lshl_add_u64 v[2:3], v[4:5], 0, v[2:3]
	v_lshl_add_u64 v[2:3], v[2:3], 0, v[84:85]
	global_load_dwordx4 v[58:61], v[2:3], off nt
	global_load_dwordx4 v[42:45], v[2:3], off offset:1024 nt
	global_load_dwordx4 v[38:41], v[2:3], off offset:2048 nt
	global_load_dwordx4 v[34:37], v[2:3], off offset:3072 nt
	v_cmp_lt_i32_e32 vcc, s14, v6
	v_cmp_gt_i32_e64 s[10:11], s4, v96
	s_and_b64 vcc, vcc, s[10:11]
	v_readlane_b32 s57, v254, 5
	v_readlane_b32 s58, v254, 6
	v_readlane_b32 s59, v254, 7
	v_readlane_b32 s60, v254, 8
	v_readlane_b32 s61, v254, 9
	v_readlane_b32 s62, v254, 10
	v_readlane_b32 s63, v254, 11
	v_readlane_b32 s64, v254, 12
	v_readlane_b32 s65, v254, 13
	v_readlane_b32 s66, v254, 14
	v_readlane_b32 s67, v254, 15
	v_readlane_b32 s68, v254, 16
	v_readlane_b32 s69, v254, 17
	s_and_saveexec_b64 s[36:37], vcc
	s_cbranch_execz .LBB0_455
	v_readlane_b32 s10, v253, 18
	v_lshlrev_b64 v[2:3], 12, v[0:1]
	v_readlane_b32 s11, v253, 19
	v_mov_b32_e32 v85, v1
	v_cmp_gt_i32_e32 vcc, s4, v96
	v_lshl_add_u64 v[10:11], s[10:11], 0, v[2:3]
	s_mov_b64 s[10:11], 0x800000
	v_lshl_add_u64 v[8:9], v[10:11], 0, s[10:11]
	s_mov_b64 s[10:11], 0x1000000
	v_lshl_add_u64 v[6:7], v[10:11], 0, s[10:11]
	s_mov_b64 s[10:11], 0x1800000
	v_lshl_add_u64 v[4:5], v[10:11], 0, s[10:11]
	v_lshl_add_u64 v[10:11], v[10:11], 0, v[84:85]
	v_lshl_add_u64 v[16:17], v[8:9], 0, v[84:85]
	global_load_dwordx4 v[12:15], v[10:11], off
	v_lshl_add_u64 v[2:3], s[54:55], 0, v[2:3]
	global_load_dwordx4 v[16:19], v[16:17], off
	s_waitcnt vmcnt(0)
	v_pk_add_f32 v[16:17], v[12:13], v[16:17]
	v_lshl_add_u64 v[12:13], v[6:7], 0, v[84:85]
	v_pk_add_f32 v[18:19], v[14:15], v[18:19]
	global_load_dwordx4 v[12:15], v[12:13], off
	s_waitcnt vmcnt(0)
	v_pk_add_f32 v[16:17], v[16:17], v[12:13]
	v_lshl_add_u64 v[12:13], v[4:5], 0, v[84:85]
	v_pk_add_f32 v[18:19], v[18:19], v[14:15]
	global_load_dwordx4 v[12:15], v[12:13], off
	s_waitcnt vmcnt(0)
	v_pk_add_f32 v[18:19], v[18:19], v[14:15]
	v_pk_add_f32 v[16:17], v[16:17], v[12:13]
	global_load_dwordx4 v[12:15], v[68:69], off
	s_waitcnt vmcnt(0)
	v_pk_fma_f32 v[60:61], v[18:19], v[14:15], v[60:61]
	v_pk_fma_f32 v[58:59], v[16:17], v[12:13], v[58:59]
	s_and_saveexec_b64 s[38:39], vcc
	s_cbranch_execz .LBB0_448
	v_lshl_add_u64 v[12:13], v[2:3], 0, v[84:85]
	global_store_dwordx4 v[12:13], v[58:61], off

.LBB0_455:
	s_or_b64 exec, exec, s[36:37]
	v_add_u32_e32 v94, s7, v66
	v_readlane_b32 s56, v254, 4
	v_min_i32_e32 v6, s6, v94
	v_readlane_b32 s71, v254, 19
	v_ashrrev_i32_e32 v2, 31, v6
	v_add_u32_e32 v0, 0xffff8000, v6
	v_cmp_gt_i32_e32 vcc, s40, v6
	v_mov_b32_e32 v4, s55
	v_readlane_b32 s70, v254, 18
	v_mov_b32_e32 v5, s71
	v_cndmask_b32_e32 v3, 0, v2, vcc
	v_cndmask_b32_e32 v2, v0, v6, vcc
	v_cndmask_b32_e32 v5, v4, v5, vcc
	v_mov_b32_e32 v4, s54
	v_mov_b32_e32 v7, s70
	v_cndmask_b32_e32 v4, v4, v7, vcc
	v_lshlrev_b64 v[2:3], 12, v[2:3]
	v_lshl_add_u64 v[2:3], v[4:5], 0, v[2:3]
	v_mov_b32_e32 v85, v1
	v_lshl_add_u64 v[2:3], v[2:3], 0, v[84:85]
	global_load_dwordx4 v[54:57], v[2:3], off nt
	global_load_dwordx4 v[26:29], v[2:3], off offset:1024 nt
	global_load_dwordx4 v[18:21], v[2:3], off offset:2048 nt
	global_load_dwordx4 v[14:17], v[2:3], off offset:3072 nt
	v_cmp_lt_i32_e32 vcc, s14, v6
	v_cmp_gt_i32_e64 s[10:11], s4, v94
	s_and_b64 vcc, vcc, s[10:11]
	v_readlane_b32 s57, v254, 5
	v_readlane_b32 s58, v254, 6
	v_readlane_b32 s59, v254, 7
	v_readlane_b32 s60, v254, 8
	v_readlane_b32 s61, v254, 9
	v_readlane_b32 s62, v254, 10
	v_readlane_b32 s63, v254, 11
	v_readlane_b32 s64, v254, 12
	v_readlane_b32 s65, v254, 13
	v_readlane_b32 s66, v254, 14
	v_readlane_b32 s67, v254, 15
	v_readlane_b32 s68, v254, 16
	v_readlane_b32 s69, v254, 17
	s_and_saveexec_b64 s[36:37], vcc
	s_cbranch_execz .LBB0_465
	v_readlane_b32 s10, v253, 18
	v_lshlrev_b64 v[2:3], 12, v[0:1]
	v_readlane_b32 s11, v253, 19
	v_cmp_gt_i32_e32 vcc, s4, v94
	s_nop 0
	v_lshl_add_u64 v[10:11], s[10:11], 0, v[2:3]
	s_mov_b64 s[10:11], 0x800000
	v_lshl_add_u64 v[8:9], v[10:11], 0, s[10:11]
	s_mov_b64 s[10:11], 0x1000000
	v_lshl_add_u64 v[6:7], v[10:11], 0, s[10:11]
	s_mov_b64 s[10:11], 0x1800000
	v_lshl_add_u64 v[4:5], v[10:11], 0, s[10:11]
	v_lshl_add_u64 v[10:11], v[10:11], 0, v[84:85]
	v_lshl_add_u64 v[12:13], v[8:9], 0, v[84:85]
	global_load_dwordx4 v[22:25], v[10:11], off
	global_load_dwordx4 v[98:101], v[12:13], off
	v_lshl_add_u64 v[2:3], s[54:55], 0, v[2:3]
	s_waitcnt vmcnt(0)
	v_pk_add_f32 v[92:93], v[22:23], v[98:99]
	v_lshl_add_u64 v[22:23], v[6:7], 0, v[84:85]
	v_pk_add_f32 v[12:13], v[24:25], v[100:101]
	global_load_dwordx4 v[22:25], v[22:23], off
	s_waitcnt vmcnt(0)
	v_pk_add_f32 v[92:93], v[92:93], v[22:23]
	v_lshl_add_u64 v[22:23], v[4:5], 0, v[84:85]
	v_pk_add_f32 v[12:13], v[12:13], v[24:25]
	global_load_dwordx4 v[22:25], v[22:23], off
	s_waitcnt vmcnt(0)
	v_pk_add_f32 v[12:13], v[12:13], v[24:25]
	v_pk_add_f32 v[92:93], v[92:93], v[22:23]
	global_load_dwordx4 v[22:25], v[68:69], off
	s_waitcnt vmcnt(0)
	v_pk_fma_f32 v[56:57], v[12:13], v[24:25], v[56:57]
	v_pk_fma_f32 v[54:55], v[92:93], v[22:23], v[54:55]
	s_and_saveexec_b64 s[38:39], vcc
	s_cbranch_execz .LBB0_458
	v_mov_b32_e32 v85, v1
	v_lshl_add_u64 v[12:13], v[2:3], 0, v[84:85]
	global_store_dwordx4 v[12:13], v[54:57], off

.LBB0_465:
	s_or_b64 exec, exec, s[36:37]
	v_add_u32_e32 v92, s8, v66
	v_readlane_b32 s56, v254, 4
	v_min_i32_e32 v67, s6, v92
	v_readlane_b32 s71, v254, 19
	v_ashrrev_i32_e32 v2, 31, v67
	v_add_u32_e32 v0, 0xffff8000, v67
	v_cmp_gt_i32_e32 vcc, s40, v67
	v_mov_b32_e32 v4, s55
	v_readlane_b32 s70, v254, 18
	v_mov_b32_e32 v5, s71
	v_cndmask_b32_e32 v3, 0, v2, vcc
	v_cndmask_b32_e32 v2, v0, v67, vcc
	v_cndmask_b32_e32 v5, v4, v5, vcc
	v_mov_b32_e32 v4, s54
	v_mov_b32_e32 v6, s70
	v_cndmask_b32_e32 v4, v4, v6, vcc
	v_lshlrev_b64 v[2:3], 12, v[2:3]
	v_lshl_add_u64 v[2:3], v[4:5], 0, v[2:3]
	v_mov_b32_e32 v85, v1
	v_lshl_add_u64 v[2:3], v[2:3], 0, v[84:85]
	global_load_dwordx4 v[22:25], v[2:3], off nt
	global_load_dwordx4 v[10:13], v[2:3], off offset:1024 nt
	global_load_dwordx4 v[6:9], v[2:3], off offset:2048 nt
	s_nop 0
	global_load_dwordx4 v[2:5], v[2:3], off offset:3072 nt
	v_cmp_lt_i32_e32 vcc, s14, v67
	v_cmp_gt_i32_e64 s[10:11], s4, v92
	s_and_b64 vcc, vcc, s[10:11]
	v_readlane_b32 s57, v254, 5
	v_readlane_b32 s58, v254, 6
	v_readlane_b32 s59, v254, 7
	v_readlane_b32 s60, v254, 8
	v_readlane_b32 s61, v254, 9
	v_readlane_b32 s62, v254, 10
	v_readlane_b32 s63, v254, 11
	v_readlane_b32 s64, v254, 12
	v_readlane_b32 s65, v254, 13
	v_readlane_b32 s66, v254, 14
	v_readlane_b32 s67, v254, 15
	v_readlane_b32 s68, v254, 16
	v_readlane_b32 s69, v254, 17
	s_and_saveexec_b64 s[36:37], vcc
	s_cbranch_execz .LBB0_475
	v_readlane_b32 s10, v253, 18
	v_lshlrev_b64 v[98:99], 12, v[0:1]
	v_readlane_b32 s11, v253, 19
	v_cmp_gt_i32_e32 vcc, s4, v92
	s_nop 0
	v_lshl_add_u64 v[106:107], s[10:11], 0, v[98:99]
	s_mov_b64 s[10:11], 0x800000
	v_lshl_add_u64 v[104:105], v[106:107], 0, s[10:11]
	s_mov_b64 s[10:11], 0x1000000
	v_lshl_add_u64 v[102:103], v[106:107], 0, s[10:11]
	s_mov_b64 s[10:11], 0x1800000
	v_lshl_add_u64 v[100:101], v[106:107], 0, s[10:11]
	v_lshl_add_u64 v[106:107], v[106:107], 0, v[84:85]
	v_lshl_add_u64 v[118:119], v[104:105], 0, v[84:85]
	global_load_dwordx4 v[114:117], v[106:107], off
	v_lshl_add_u64 v[98:99], s[54:55], 0, v[98:99]
	global_load_dwordx4 v[118:121], v[118:119], off
	s_waitcnt vmcnt(0)
	v_pk_add_f32 v[118:119], v[114:115], v[118:119]
	v_lshl_add_u64 v[114:115], v[102:103], 0, v[84:85]
	v_pk_add_f32 v[120:121], v[116:117], v[120:121]
	global_load_dwordx4 v[114:117], v[114:115], off
	s_waitcnt vmcnt(0)
	v_pk_add_f32 v[118:119], v[118:119], v[114:115]
	v_lshl_add_u64 v[114:115], v[100:101], 0, v[84:85]
	v_pk_add_f32 v[120:121], v[120:121], v[116:117]
	global_load_dwordx4 v[114:117], v[114:115], off
	s_waitcnt vmcnt(0)
	v_pk_add_f32 v[120:121], v[120:121], v[116:117]
	v_pk_add_f32 v[118:119], v[118:119], v[114:115]
	global_load_dwordx4 v[114:117], v[68:69], off
	s_waitcnt vmcnt(0)
	v_pk_fma_f32 v[24:25], v[120:121], v[116:117], v[24:25]
	v_pk_fma_f32 v[22:23], v[118:119], v[114:115], v[22:23]
	s_and_saveexec_b64 s[38:39], vcc
	s_cbranch_execz .LBB0_468
	v_mov_b32_e32 v85, v1
	v_lshl_add_u64 v[114:115], v[98:99], 0, v[84:85]
	global_store_dwordx4 v[114:115], v[22:25], off

.LBB0_519:
	s_min_i32 s25, s47, 0x80
	s_lshr_b32 s25, s25, 4
	s_mul_i32 s40, s25, 0x1800
	s_ashr_i32 s41, s40, 31
	s_lshl_b64 s[40:41], s[40:41], 2
	s_add_u32 s42, s18, s40
	s_addc_u32 s43, s19, s41
	s_cmpk_lt_i32 s47, 0x80
	v_lshl_add_u32 v146, s47, 18, v143
	v_add_u32_e32 v0, 0xfe000000, v146
	s_cselect_b64 vcc, -1, 0
	v_lshl_or_b32 v140, s46, 8, v144
	v_cndmask_b32_e32 v147, v0, v146, vcc
	s_and_b64 s[40:41], vcc, exec
	v_add_u32_e32 v0, v147, v140
	s_cselect_b32 s41, s15, s55
	s_cselect_b32 s40, s16, s54
	v_lshlrev_b64 v[152:153], 2, v[0:1]
	v_mov_b32_e32 v141, v1
	v_lshl_add_u64 v[146:147], s[40:41], 0, v[152:153]
	v_lshl_add_u64 v[138:139], v[140:141], 2, s[42:43]
	global_load_dwordx4 v[172:175], v[138:139], off
	global_load_dwordx4 v[176:179], v[138:139], off offset:64
	global_load_dwordx4 v[180:183], v[138:139], off offset:512
	global_load_dwordx4 v[184:187], v[138:139], off offset:576
	v_readlane_b32 s56, v254, 4
	v_readlane_b32 s70, v254, 18
	v_readlane_b32 s71, v254, 19
	s_cselect_b32 s43, s71, s55
	s_cselect_b32 s42, s70, s54
	v_lshl_add_u64 v[152:153], s[42:43], 0, v[152:153]
	v_readlane_b32 s57, v254, 5
	v_readlane_b32 s58, v254, 6
	v_readlane_b32 s59, v254, 7
	v_readlane_b32 s60, v254, 8
	v_readlane_b32 s61, v254, 9
	v_readlane_b32 s62, v254, 10
	v_readlane_b32 s63, v254, 11
	v_readlane_b32 s64, v254, 12
	v_readlane_b32 s65, v254, 13
	v_readlane_b32 s66, v254, 14
	v_readlane_b32 s67, v254, 15
	v_readlane_b32 s68, v254, 16
	v_readlane_b32 s69, v254, 17
	s_mov_b64 s[40:41], 0x10000
	s_mov_b64 s[42:43], 0x50000
	global_load_dwordx4 v[148:151], v[146:147], off
	global_load_dwordx4 v[168:171], v[146:147], off offset:64
	global_load_dwordx4 v[188:191], v[146:147], off offset:512
	global_load_dwordx4 v[192:195], v[146:147], off offset:576
	v_lshl_add_u64 v[146:147], v[146:147], 0, s[40:41]
	global_load_dwordx4 v[196:199], v[146:147], off
	global_load_dwordx4 v[200:203], v[146:147], off offset:64
	global_load_dwordx4 v[204:207], v[146:147], off offset:512
	global_load_dwordx4 v[208:211], v[146:147], off offset:576
	v_lshl_add_u64 v[146:147], v[146:147], 0, s[40:41]
	global_load_dwordx4 v[212:215], v[146:147], off
	global_load_dwordx4 v[224:227], v[146:147], off offset:64
	global_load_dwordx4 v[234:237], v[146:147], off offset:512
	global_load_dwordx4 v[238:241], v[146:147], off offset:576
	s_waitcnt vmcnt(11)
	v_pk_fma_f32 v[128:129], v[128:129], v[174:175], v[150:151]
	v_pk_fma_f32 v[126:127], v[126:127], v[172:173], v[148:149]
	global_store_dwordx4 v[152:153], v[126:129], off
	v_lshl_add_u64 v[146:147], v[146:147], 0, s[40:41]
	global_load_dwordx4 v[148:151], v[146:147], off
	s_waitcnt vmcnt(12)
	v_pk_fma_f32 v[124:125], v[124:125], v[178:179], v[170:171]
	v_pk_fma_f32 v[122:123], v[122:123], v[176:177], v[168:169]
	global_store_dwordx4 v[152:153], v[122:125], off offset:64
	global_load_dwordx4 v[168:171], v[146:147], off offset:64
	s_waitcnt vmcnt(13)
	v_pk_fma_f32 v[120:121], v[120:121], v[182:183], v[190:191]
	v_pk_fma_f32 v[118:119], v[118:119], v[180:181], v[188:189]
	global_store_dwordx4 v[152:153], v[118:121], off offset:512
	global_load_dwordx4 v[188:191], v[146:147], off offset:512
	s_waitcnt vmcnt(14)
	v_pk_fma_f32 v[112:113], v[112:113], v[186:187], v[194:195]
	v_pk_fma_f32 v[110:111], v[110:111], v[184:185], v[192:193]
	global_store_dwordx4 v[152:153], v[110:113], off offset:576
	global_load_dwordx4 v[192:195], v[146:147], off offset:576
	s_waitcnt vmcnt(15)
	v_pk_fma_f32 v[116:117], v[116:117], v[174:175], v[198:199]
	v_pk_fma_f32 v[114:115], v[114:115], v[172:173], v[196:197]
	v_lshl_add_u64 v[152:153], v[152:153], 0, s[40:41]
	global_store_dwordx4 v[152:153], v[114:117], off
	v_lshl_add_u64 v[146:147], v[146:147], 0, s[42:43]
	global_load_dwordx4 v[196:199], v[146:147], off
	s_waitcnt vmcnt(16)
	v_pk_fma_f32 v[108:109], v[108:109], v[178:179], v[202:203]
	v_pk_fma_f32 v[106:107], v[106:107], v[176:177], v[200:201]
	global_store_dwordx4 v[152:153], v[106:109], off offset:64
	global_load_dwordx4 v[200:203], v[146:147], off offset:64
	s_waitcnt vmcnt(17)
	v_pk_fma_f32 v[104:105], v[104:105], v[182:183], v[206:207]
	v_pk_fma_f32 v[102:103], v[102:103], v[180:181], v[204:205]
	global_store_dwordx4 v[152:153], v[102:105], off offset:512
	global_load_dwordx4 v[204:207], v[146:147], off offset:512
	s_waitcnt vmcnt(18)
	v_pk_fma_f32 v[96:97], v[96:97], v[186:187], v[210:211]
	v_pk_fma_f32 v[94:95], v[94:95], v[184:185], v[208:209]
	global_store_dwordx4 v[152:153], v[94:97], off offset:576
	global_load_dwordx4 v[208:211], v[146:147], off offset:576
	s_waitcnt vmcnt(19)
	v_pk_fma_f32 v[100:101], v[100:101], v[174:175], v[214:215]
	v_pk_fma_f32 v[98:99], v[98:99], v[172:173], v[212:213]
	v_lshl_add_u64 v[152:153], v[152:153], 0, s[40:41]
	global_store_dwordx4 v[152:153], v[98:101], off
	v_lshl_add_u64 v[146:147], v[146:147], 0, s[40:41]
	global_load_dwordx4 v[212:215], v[146:147], off
	s_waitcnt vmcnt(20)
	v_pk_fma_f32 v[92:93], v[92:93], v[178:179], v[226:227]
	v_pk_fma_f32 v[90:91], v[90:91], v[176:177], v[224:225]
	global_store_dwordx4 v[152:153], v[90:93], off offset:64
	global_load_dwordx4 v[224:227], v[146:147], off offset:64
	s_waitcnt vmcnt(21)
	v_pk_fma_f32 v[88:89], v[88:89], v[182:183], v[236:237]
	v_pk_fma_f32 v[86:87], v[86:87], v[180:181], v[234:235]
	global_store_dwordx4 v[152:153], v[86:89], off offset:512
	global_load_dwordx4 v[234:237], v[146:147], off offset:512
	s_waitcnt vmcnt(22)
	v_pk_fma_f32 v[80:81], v[80:81], v[186:187], v[240:241]
	v_pk_fma_f32 v[78:79], v[78:79], v[184:185], v[238:239]
	global_store_dwordx4 v[152:153], v[78:81], off offset:576
	global_load_dwordx4 v[238:241], v[146:147], off offset:576
	s_waitcnt vmcnt(22)
	v_pk_fma_f32 v[84:85], v[84:85], v[174:175], v[150:151]
	v_pk_fma_f32 v[82:83], v[82:83], v[172:173], v[148:149]
	v_lshl_add_u64 v[152:153], v[152:153], 0, s[40:41]
	global_store_dwordx4 v[152:153], v[82:85], off
	v_lshl_add_u64 v[146:147], v[146:147], 0, s[40:41]
	global_load_dwordx4 v[148:151], v[146:147], off
	s_waitcnt vmcnt(22)
	v_pk_fma_f32 v[76:77], v[76:77], v[178:179], v[170:171]
	v_pk_fma_f32 v[74:75], v[74:75], v[176:177], v[168:169]
	global_store_dwordx4 v[152:153], v[74:77], off offset:64
	global_load_dwordx4 v[168:171], v[146:147], off offset:64
	s_waitcnt vmcnt(22)
	v_pk_fma_f32 v[72:73], v[72:73], v[182:183], v[190:191]
	v_pk_fma_f32 v[70:71], v[70:71], v[180:181], v[188:189]
	global_store_dwordx4 v[152:153], v[70:73], off offset:512
	global_load_dwordx4 v[188:191], v[146:147], off offset:512
	s_waitcnt vmcnt(22)
	v_pk_fma_f32 v[68:69], v[68:69], v[186:187], v[194:195]
	v_pk_fma_f32 v[66:67], v[66:67], v[184:185], v[192:193]
	global_store_dwordx4 v[152:153], v[66:69], off offset:576
	global_load_dwordx4 v[192:195], v[146:147], off offset:576
	s_waitcnt vmcnt(22)
	v_pk_fma_f32 v[64:65], v[64:65], v[174:175], v[198:199]
	v_pk_fma_f32 v[62:63], v[62:63], v[172:173], v[196:197]
	v_lshl_add_u64 v[152:153], v[152:153], 0, s[42:43]
	global_store_dwordx4 v[152:153], v[62:65], off
	v_lshl_add_u64 v[146:147], v[146:147], 0, s[40:41]
	global_load_dwordx4 v[196:199], v[146:147], off
	s_waitcnt vmcnt(22)
	v_pk_fma_f32 v[60:61], v[60:61], v[178:179], v[202:203]
	v_pk_fma_f32 v[58:59], v[58:59], v[176:177], v[200:201]
	global_store_dwordx4 v[152:153], v[58:61], off offset:64
	global_load_dwordx4 v[200:203], v[146:147], off offset:64
	s_waitcnt vmcnt(22)
	v_pk_fma_f32 v[56:57], v[56:57], v[182:183], v[206:207]
	v_pk_fma_f32 v[54:55], v[54:55], v[180:181], v[204:205]
	global_store_dwordx4 v[152:153], v[54:57], off offset:512
	global_load_dwordx4 v[204:207], v[146:147], off offset:512
	s_waitcnt vmcnt(22)
	v_pk_fma_f32 v[48:49], v[48:49], v[186:187], v[210:211]
	v_pk_fma_f32 v[46:47], v[46:47], v[184:185], v[208:209]
	global_store_dwordx4 v[152:153], v[46:49], off offset:576
	global_load_dwordx4 v[208:211], v[146:147], off offset:576
	s_waitcnt vmcnt(22)
	v_pk_fma_f32 v[52:53], v[52:53], v[174:175], v[214:215]
	v_pk_fma_f32 v[50:51], v[50:51], v[172:173], v[212:213]
	v_lshl_add_u64 v[152:153], v[152:153], 0, s[40:41]
	global_store_dwordx4 v[152:153], v[50:53], off
	s_waitcnt vmcnt(21)
	v_pk_fma_f32 v[44:45], v[44:45], v[178:179], v[226:227]
	v_pk_fma_f32 v[42:43], v[42:43], v[176:177], v[224:225]
	global_store_dwordx4 v[152:153], v[42:45], off offset:64
	s_waitcnt vmcnt(20)
	v_pk_fma_f32 v[40:41], v[40:41], v[182:183], v[236:237]
	v_pk_fma_f32 v[38:39], v[38:39], v[180:181], v[234:235]
	global_store_dwordx4 v[152:153], v[38:41], off offset:512
	s_waitcnt vmcnt(19)
	v_pk_fma_f32 v[32:33], v[32:33], v[186:187], v[240:241]
	v_pk_fma_f32 v[30:31], v[30:31], v[184:185], v[238:239]
	global_store_dwordx4 v[152:153], v[30:33], off offset:576
	s_waitcnt vmcnt(18)
	v_pk_fma_f32 v[36:37], v[36:37], v[174:175], v[150:151]
	v_pk_fma_f32 v[34:35], v[34:35], v[172:173], v[148:149]
	v_lshl_add_u64 v[152:153], v[152:153], 0, s[40:41]
	global_store_dwordx4 v[152:153], v[34:37], off
	s_waitcnt vmcnt(17)
	v_pk_fma_f32 v[28:29], v[28:29], v[178:179], v[170:171]
	v_pk_fma_f32 v[26:27], v[26:27], v[176:177], v[168:169]
	global_store_dwordx4 v[152:153], v[26:29], off offset:64
	s_waitcnt vmcnt(16)
	v_pk_fma_f32 v[24:25], v[24:25], v[182:183], v[190:191]
	v_pk_fma_f32 v[22:23], v[22:23], v[180:181], v[188:189]
	global_store_dwordx4 v[152:153], v[22:25], off offset:512
	s_waitcnt vmcnt(15)
	v_pk_fma_f32 v[16:17], v[16:17], v[186:187], v[194:195]
	v_pk_fma_f32 v[14:15], v[14:15], v[184:185], v[192:193]
	global_store_dwordx4 v[152:153], v[14:17], off offset:576
	s_waitcnt vmcnt(14)
	v_pk_fma_f32 v[20:21], v[20:21], v[174:175], v[198:199]
	v_pk_fma_f32 v[18:19], v[18:19], v[172:173], v[196:197]
	v_lshl_add_u64 v[152:153], v[152:153], 0, s[40:41]
	global_store_dwordx4 v[152:153], v[18:21], off
	s_waitcnt vmcnt(13)
	v_pk_fma_f32 v[12:13], v[12:13], v[178:179], v[202:203]
	v_pk_fma_f32 v[10:11], v[10:11], v[176:177], v[200:201]
	global_store_dwordx4 v[152:153], v[10:13], off offset:64
	s_waitcnt vmcnt(12)
	v_pk_fma_f32 v[8:9], v[8:9], v[182:183], v[206:207]
	v_pk_fma_f32 v[6:7], v[6:7], v[180:181], v[204:205]
	global_store_dwordx4 v[152:153], v[6:9], off offset:512
	s_waitcnt vmcnt(11)
	v_pk_fma_f32 v[4:5], v[4:5], v[186:187], v[210:211]
	v_pk_fma_f32 v[2:3], v[2:3], v[184:185], v[208:209]
	global_store_dwordx4 v[152:153], v[2:5], off offset:576
	s_andn2_b64 vcc, exec, s[38:39]
	s_mov_b64 s[38:39], -1
	s_cbranch_vccnz .LBB0_508
	s_andn2_b64 vcc, exec, s[2:3]
	s_cbranch_vccnz .LBB0_507
	s_barrier
	s_branch .LBB0_507

.LBB0_532:
	s_or_b64 exec, exec, s[34:35]
	v_add_u32_e32 v86, s4, v66
	v_min_i32_e32 v10, 0x87ff, v86
	v_ashrrev_i32_e32 v11, 31, v10
	v_add_u32_e32 v0, 0xffff8000, v10
	v_cmp_gt_i32_e32 vcc, s40, v86
	v_mov_b32_e32 v12, s55
	v_mov_b32_e32 v13, s48
	v_cndmask_b32_e32 v11, 0, v11, vcc
	v_cndmask_b32_e32 v10, v0, v10, vcc
	v_cndmask_b32_e32 v13, v12, v13, vcc
	v_mov_b32_e32 v12, s54
	v_mov_b32_e32 v14, s49
	v_cndmask_b32_e32 v12, v12, v14, vcc
	v_lshlrev_b64 v[10:11], 12, v[10:11]
	v_lshl_add_u64 v[10:11], v[12:13], 0, v[10:11]
	v_lshl_add_u64 v[10:11], v[10:11], 0, v[78:79]
	global_load_dwordx4 v[34:37], v[10:11], off nt
	global_load_dwordx4 v[30:33], v[10:11], off offset:1024 nt
	global_load_dwordx4 v[18:21], v[10:11], off offset:2048 nt
	s_nop 0
	global_load_dwordx4 v[10:13], v[10:11], off offset:3072 nt
	v_cmp_lt_i32_e32 vcc, s14, v86
	s_mov_b32 s8, 0x8800
	v_cmp_gt_i32_e64 s[8:9], s8, v86
	s_and_b64 vcc, vcc, s[8:9]
	s_and_b64 s[8:9], s[22:23], vcc
	s_and_saveexec_b64 s[34:35], s[8:9]
	s_cbranch_execz .LBB0_542
	v_readlane_b32 s8, v253, 18
	v_lshlrev_b64 v[14:15], 12, v[0:1]
	v_readlane_b32 s9, v253, 19
	v_mov_b32_e32 v79, v1
	v_cmp_gt_u32_e32 vcc, s15, v86
	v_lshl_add_u64 v[42:43], s[8:9], 0, v[14:15]
	s_mov_b64 s[8:9], 0x800000
	v_lshl_add_u64 v[28:29], v[42:43], 0, s[8:9]
	s_mov_b64 s[8:9], 0x1000000
	v_lshl_add_u64 v[26:27], v[42:43], 0, s[8:9]
	s_mov_b64 s[8:9], 0x1800000
	v_lshl_add_u64 v[16:17], v[42:43], 0, s[8:9]
	v_lshl_add_u64 v[42:43], v[42:43], 0, v[78:79]
	v_lshl_add_u64 v[48:49], v[28:29], 0, v[78:79]
	global_load_dwordx4 v[44:47], v[42:43], off
	s_nop 0
	global_load_dwordx4 v[48:51], v[48:49], off
	v_lshl_add_u64 v[52:53], v[26:27], 0, v[78:79]
	global_load_dwordx4 v[52:55], v[52:53], off
	v_lshl_add_u64 v[56:57], v[16:17], 0, v[78:79]
	global_load_dwordx4 v[56:59], v[56:57], off
	s_nop 0
	global_load_dwordx4 v[60:63], v[68:69], off
	v_lshl_add_u64 v[14:15], s[54:55], 0, v[14:15]
	s_waitcnt vmcnt(0)
	v_pk_add_f32 v[46:47], v[46:47], v[50:51]
	v_pk_add_f32 v[44:45], v[44:45], v[48:49]
	v_pk_add_f32 v[46:47], v[46:47], v[54:55]
	v_pk_add_f32 v[44:45], v[44:45], v[52:53]
	v_pk_add_f32 v[46:47], v[46:47], v[58:59]
	v_pk_add_f32 v[44:45], v[44:45], v[56:57]
	v_pk_fma_f32 v[36:37], v[46:47], v[62:63], v[36:37]
	v_pk_fma_f32 v[34:35], v[44:45], v[60:61], v[34:35]
	s_and_saveexec_b64 s[36:37], vcc
	s_cbranch_execz .LBB0_535
	v_lshl_add_u64 v[44:45], v[14:15], 0, v[78:79]
	global_store_dwordx4 v[44:45], v[34:37], off

.LBB0_542:
	s_or_b64 exec, exec, s[34:35]
	v_add_u32_e32 v88, s5, v66
	v_min_i32_e32 v14, 0x87ff, v88
	v_ashrrev_i32_e32 v15, 31, v14
	v_add_u32_e32 v0, 0xffff8000, v14
	v_cmp_gt_i32_e32 vcc, s40, v88
	v_mov_b32_e32 v16, s55
	v_mov_b32_e32 v17, s48
	v_cndmask_b32_e32 v15, 0, v15, vcc
	v_cndmask_b32_e32 v14, v0, v14, vcc
	v_cndmask_b32_e32 v17, v16, v17, vcc
	v_mov_b32_e32 v16, s54
	v_mov_b32_e32 v26, s49
	v_cndmask_b32_e32 v16, v16, v26, vcc
	v_lshlrev_b64 v[14:15], 12, v[14:15]
	v_lshl_add_u64 v[14:15], v[16:17], 0, v[14:15]
	v_mov_b32_e32 v79, v1
	v_lshl_add_u64 v[14:15], v[14:15], 0, v[78:79]
	global_load_dwordx4 v[46:49], v[14:15], off nt
	global_load_dwordx4 v[42:45], v[14:15], off offset:1024 nt
	global_load_dwordx4 v[26:29], v[14:15], off offset:2048 nt
	s_nop 0
	global_load_dwordx4 v[14:17], v[14:15], off offset:3072 nt
	v_cmp_lt_i32_e32 vcc, s14, v88
	s_mov_b32 s8, 0x8800
	v_cmp_gt_i32_e64 s[8:9], s8, v88
	s_and_b64 vcc, vcc, s[8:9]
	s_and_b64 s[8:9], s[22:23], vcc
	s_and_saveexec_b64 s[34:35], s[8:9]
	s_cbranch_execz .LBB0_552
	v_readlane_b32 s8, v253, 18
	v_lshlrev_b64 v[50:51], 12, v[0:1]
	v_readlane_b32 s9, v253, 19
	v_cmp_gt_u32_e32 vcc, s15, v88
	s_nop 0
	v_lshl_add_u64 v[58:59], s[8:9], 0, v[50:51]
	s_mov_b64 s[8:9], 0x800000
	v_lshl_add_u64 v[56:57], v[58:59], 0, s[8:9]
	s_mov_b64 s[8:9], 0x1000000
	v_lshl_add_u64 v[54:55], v[58:59], 0, s[8:9]
	s_mov_b64 s[8:9], 0x1800000
	v_lshl_add_u64 v[52:53], v[58:59], 0, s[8:9]
	v_lshl_add_u64 v[58:59], v[58:59], 0, v[78:79]
	v_lshl_add_u64 v[64:65], v[56:57], 0, v[78:79]
	global_load_dwordx4 v[60:63], v[58:59], off
	global_load_dwordx4 v[90:93], v[64:65], off
	v_lshl_add_u64 v[50:51], s[54:55], 0, v[50:51]
	s_waitcnt vmcnt(0)
	v_pk_add_f32 v[90:91], v[60:61], v[90:91]
	v_lshl_add_u64 v[60:61], v[54:55], 0, v[78:79]
	v_pk_add_f32 v[64:65], v[62:63], v[92:93]
	global_load_dwordx4 v[60:63], v[60:61], off
	s_waitcnt vmcnt(0)
	v_pk_add_f32 v[90:91], v[90:91], v[60:61]
	v_lshl_add_u64 v[60:61], v[52:53], 0, v[78:79]
	v_pk_add_f32 v[64:65], v[64:65], v[62:63]
	global_load_dwordx4 v[60:63], v[60:61], off
	s_waitcnt vmcnt(0)
	v_pk_add_f32 v[64:65], v[64:65], v[62:63]
	v_pk_add_f32 v[90:91], v[90:91], v[60:61]
	global_load_dwordx4 v[60:63], v[68:69], off
	s_waitcnt vmcnt(0)
	v_pk_fma_f32 v[48:49], v[64:65], v[62:63], v[48:49]
	v_pk_fma_f32 v[46:47], v[90:91], v[60:61], v[46:47]
	s_and_saveexec_b64 s[36:37], vcc
	s_cbranch_execz .LBB0_545
	v_mov_b32_e32 v79, v1
	v_lshl_add_u64 v[60:61], v[50:51], 0, v[78:79]
	global_store_dwordx4 v[60:61], v[46:49], off

.LBB0_552:
	s_or_b64 exec, exec, s[34:35]
	v_add_u32_e32 v90, s6, v66
	v_min_i32_e32 v50, 0x87ff, v90
	v_ashrrev_i32_e32 v51, 31, v50
	v_add_u32_e32 v0, 0xffff8000, v50
	v_cmp_gt_i32_e32 vcc, s40, v90
	v_mov_b32_e32 v52, s55
	v_mov_b32_e32 v53, s48
	v_cndmask_b32_e32 v51, 0, v51, vcc
	v_cndmask_b32_e32 v50, v0, v50, vcc
	v_cndmask_b32_e32 v53, v52, v53, vcc
	v_mov_b32_e32 v52, s54
	v_mov_b32_e32 v54, s49
	v_cndmask_b32_e32 v52, v52, v54, vcc
	v_lshlrev_b64 v[50:51], 12, v[50:51]
	v_lshl_add_u64 v[50:51], v[52:53], 0, v[50:51]
	v_mov_b32_e32 v79, v1
	v_lshl_add_u64 v[50:51], v[50:51], 0, v[78:79]
	global_load_dwordx4 v[62:65], v[50:51], off nt
	global_load_dwordx4 v[58:61], v[50:51], off offset:1024 nt
	global_load_dwordx4 v[54:57], v[50:51], off offset:2048 nt
	s_nop 0
	global_load_dwordx4 v[50:53], v[50:51], off offset:3072 nt
	v_cmp_lt_i32_e32 vcc, s14, v90
	s_mov_b32 s8, 0x8800
	v_cmp_gt_i32_e64 s[8:9], s8, v90
	s_and_b64 vcc, vcc, s[8:9]
	s_and_b64 s[8:9], s[22:23], vcc
	s_and_saveexec_b64 s[34:35], s[8:9]
	s_cbranch_execz .LBB0_562
	v_readlane_b32 s8, v253, 18
	v_lshlrev_b64 v[92:93], 12, v[0:1]
	v_readlane_b32 s9, v253, 19
	v_cmp_gt_u32_e32 vcc, s15, v90
	s_nop 0
	v_lshl_add_u64 v[100:101], s[8:9], 0, v[92:93]
	s_mov_b64 s[8:9], 0x800000
	v_lshl_add_u64 v[98:99], v[100:101], 0, s[8:9]
	s_mov_b64 s[8:9], 0x1000000
	v_lshl_add_u64 v[96:97], v[100:101], 0, s[8:9]
	s_mov_b64 s[8:9], 0x1800000
	v_lshl_add_u64 v[94:95], v[100:101], 0, s[8:9]
	v_lshl_add_u64 v[100:101], v[100:101], 0, v[78:79]
	v_lshl_add_u64 v[112:113], v[98:99], 0, v[78:79]
	global_load_dwordx4 v[108:111], v[100:101], off
	s_nop 0
	global_load_dwordx4 v[112:115], v[112:113], off
	v_lshl_add_u64 v[116:117], v[96:97], 0, v[78:79]
	global_load_dwordx4 v[116:119], v[116:117], off
	v_lshl_add_u64 v[120:121], v[94:95], 0, v[78:79]
	global_load_dwordx4 v[120:123], v[120:121], off
	s_nop 0
	global_load_dwordx4 v[124:127], v[68:69], off
	v_lshl_add_u64 v[92:93], s[54:55], 0, v[92:93]
	s_waitcnt vmcnt(0)
	v_pk_add_f32 v[110:111], v[110:111], v[114:115]
	v_pk_add_f32 v[108:109], v[108:109], v[112:113]
	v_pk_add_f32 v[110:111], v[110:111], v[118:119]
	v_pk_add_f32 v[108:109], v[108:109], v[116:117]
	v_pk_add_f32 v[110:111], v[110:111], v[122:123]
	v_pk_add_f32 v[108:109], v[108:109], v[120:121]
	v_pk_fma_f32 v[64:65], v[110:111], v[126:127], v[64:65]
	v_pk_fma_f32 v[62:63], v[108:109], v[124:125], v[62:63]
	s_and_saveexec_b64 s[36:37], vcc
	s_cbranch_execz .LBB0_555
	v_mov_b32_e32 v79, v1
	v_lshl_add_u64 v[108:109], v[92:93], 0, v[78:79]
	global_store_dwordx4 v[108:109], v[62:65], off
